# same as v35 but the static s_setprio 1 goes to waves 0-3 (the leading half) instead of waves 4-7
# baseline (speedup 1.0000x reference)
;     __device__ bool next(int i, Unit& u) const { const int L = i * G + c; if (L >= 512) return false; u.pm = 0; u.pn = L; u.offA = 0; u.offB = (size_t)L * 256 * 256 * 2; return true; }
; template <class Epi, class Sched>
; __device__ __forceinline__ void gemm_phase(LAS unsigned char* lds, const Gemm g, const Sched& S, const Epi& E) {
;     ...
;         const bool has_next = S.next(ui + 1, nxt);
;         const char* nA = has_next ? (const char*)g.A + nxt.offA : cA; const char* nB = has_next ? (const char*)g.Bt + nxt.offB : cB;
;         for (int t = 0; t < nt; t += 2) {
;             const bool last = (t == nt - 2);
;             const char* a1 = cA + (size_t)(t + 1) * kstep;
;             const char* a2 = last ? nA : cA + (size_t)(t + 2) * kstep; const char* b2 = last ? nB : cB + (size_t)(t + 2) * kstep;
;             const char* a3 = a2 + kstep; const char* b3 = b2 + kstep;
;     ...
; #pragma unroll
;         for (int a = 0; a < 2; ++a)
; #pragma unroll
;             for (int b = 0; b < 2; ++b)
; #pragma unroll
;                 for (int m = 0; m < 4; ++m)
; #pragma unroll
;                     for (int n = 0; n < 2; ++n) acc[a][b][m][n] = (f32x4){0.f, 0.f, 0.f, 0.f};
.LBB0_220:
	s_add_u32 s50, s2, s46
	s_addc_u32 s51, s3, s47
	s_add_u32 s76, s7, s48
	s_addc_u32 s77, s11, s49
	s_andn2_b64 vcc, exec, s[74:75]
	s_cbranch_vccnz .Lzc_6242
	s_and_b64 s[8:9], s[36:37], exec
	s_cselect_b32 s10, s51, s1
	s_cselect_b32 s43, s50, s0
	s_cselect_b32 s45, s77, s39
	s_cselect_b32 vcc_lo, s76, s38
	s_add_u32 s0, s0, 0x40080
	s_addc_u32 s1, s1, 0
	s_add_u32 vcc_hi, s38, 0x100
	v_mov_b32_e32 v6, 0
	s_mov_b64 s[22:23], s[74:75]
	s_addc_u32 s8, s39, 0
	s_mov_b32 s9, 0
	v_mov_b32_e32 v7, v6
	v_mov_b32_e32 v8, v6
	v_mov_b32_e32 v9, v6
	v_mov_b32_e32 v14, v6
	v_mov_b32_e32 v15, v6
	v_mov_b32_e32 v16, v6
	v_mov_b32_e32 v17, v6
	v_mov_b32_e32 v22, v6
	v_mov_b32_e32 v23, v6
	v_mov_b32_e32 v24, v6
	v_mov_b32_e32 v25, v6
	v_mov_b32_e32 v30, v6
	v_mov_b32_e32 v31, v6
	v_mov_b32_e32 v32, v6
	v_mov_b32_e32 v33, v6
	v_mov_b32_e32 v38, v6
	v_mov_b32_e32 v39, v6
	v_mov_b32_e32 v40, v6
	v_mov_b32_e32 v41, v6
	v_mov_b32_e32 v46, v6
	v_mov_b32_e32 v47, v6
	v_mov_b32_e32 v48, v6
	v_mov_b32_e32 v49, v6
	v_mov_b32_e32 v54, v6
	v_mov_b32_e32 v55, v6
	v_mov_b32_e32 v56, v6
	v_mov_b32_e32 v57, v6
	v_mov_b32_e32 v62, v6
	v_mov_b32_e32 v63, v6
	v_mov_b32_e32 v64, v6
	v_mov_b32_e32 v65, v6
	v_mov_b32_e32 v2, v6
	v_mov_b32_e32 v3, v6
	v_mov_b32_e32 v4, v6
	v_mov_b32_e32 v5, v6
	v_mov_b32_e32 v10, v6
	v_mov_b32_e32 v11, v6
	v_mov_b32_e32 v12, v6
	v_mov_b32_e32 v13, v6
	v_mov_b32_e32 v18, v6
	v_mov_b32_e32 v19, v6
	v_mov_b32_e32 v20, v6
	v_mov_b32_e32 v21, v6
	v_mov_b32_e32 v26, v6
	v_mov_b32_e32 v27, v6
	v_mov_b32_e32 v28, v6
	v_mov_b32_e32 v29, v6
	v_mov_b32_e32 v34, v6
	v_mov_b32_e32 v35, v6
	v_mov_b32_e32 v36, v6
	v_mov_b32_e32 v37, v6
	v_mov_b32_e32 v42, v6
	v_mov_b32_e32 v43, v6
	v_mov_b32_e32 v44, v6
	v_mov_b32_e32 v45, v6
	v_mov_b32_e32 v50, v6
	v_mov_b32_e32 v51, v6
	v_mov_b32_e32 v52, v6
	v_mov_b32_e32 v53, v6
	v_mov_b32_e32 v58, v6
	v_mov_b32_e32 v59, v6
	v_mov_b32_e32 v60, v6
	v_mov_b32_e32 v61, v6
	v_mov_b32_e32 v70, v6
	v_mov_b32_e32 v71, v6
	v_mov_b32_e32 v72, v6
	v_mov_b32_e32 v73, v6
	v_mov_b32_e32 v78, v6
	v_mov_b32_e32 v79, v6
	v_mov_b32_e32 v80, v6
	v_mov_b32_e32 v81, v6
	v_mov_b32_e32 v86, v6
	v_mov_b32_e32 v87, v6
	v_mov_b32_e32 v88, v6
	v_mov_b32_e32 v89, v6
	v_mov_b32_e32 v94, v6
	v_mov_b32_e32 v95, v6
	v_mov_b32_e32 v96, v6
	v_mov_b32_e32 v97, v6
	v_mov_b32_e32 v102, v6
	v_mov_b32_e32 v103, v6
	v_mov_b32_e32 v104, v6
	v_mov_b32_e32 v105, v6
	v_mov_b32_e32 v110, v6
	v_mov_b32_e32 v111, v6
	v_mov_b32_e32 v112, v6
	v_mov_b32_e32 v113, v6
	v_mov_b32_e32 v118, v6
	v_mov_b32_e32 v119, v6
	v_mov_b32_e32 v120, v6
	v_mov_b32_e32 v121, v6
	v_mov_b32_e32 v126, v6
	v_mov_b32_e32 v127, v6
	v_mov_b32_e32 v128, v6
	v_mov_b32_e32 v129, v6
	v_mov_b32_e32 v66, v6
	v_mov_b32_e32 v67, v6
	v_mov_b32_e32 v68, v6
	v_mov_b32_e32 v69, v6
	v_mov_b32_e32 v74, v6
	v_mov_b32_e32 v75, v6
	v_mov_b32_e32 v76, v6
	v_mov_b32_e32 v77, v6
	v_mov_b32_e32 v82, v6
	v_mov_b32_e32 v83, v6
	v_mov_b32_e32 v84, v6
	v_mov_b32_e32 v85, v6
	v_mov_b32_e32 v90, v6
	v_mov_b32_e32 v91, v6
	v_mov_b32_e32 v92, v6
	v_mov_b32_e32 v93, v6
	v_mov_b32_e32 v98, v6
	v_mov_b32_e32 v99, v6
	v_mov_b32_e32 v100, v6
	v_mov_b32_e32 v101, v6
	v_mov_b32_e32 v106, v6
	v_mov_b32_e32 v107, v6
	v_mov_b32_e32 v108, v6
	v_mov_b32_e32 v109, v6
	v_mov_b32_e32 v114, v6
	v_mov_b32_e32 v115, v6
	v_mov_b32_e32 v116, v6
	v_mov_b32_e32 v117, v6
	v_mov_b32_e32 v122, v6
	v_mov_b32_e32 v123, v6
	v_mov_b32_e32 v124, v6
	v_mov_b32_e32 v125, v6
	v_readfirstlane_b32 s96, v193
	s_lshr_b32 s96, s96, 8
	s_cmp_eq_u32 s96, 0
	s_cbranch_scc0 .Lnp_222
	s_setprio 1

;     __device__ bool next(int i, Unit& u) const { const int L = i * G + c; if (L >= 512) return false; u.pm = 0; u.pn = L; u.offA = 0; u.offB = (size_t)L * 256 * 256 * 2; return true; }
; template <class Epi, class Sched>
; __device__ __forceinline__ void gemm_phase(LAS unsigned char* lds, const Gemm g, const Sched& S, const Epi& E) {
;     ...
;         const bool has_next = S.next(ui + 1, nxt);
;         const char* nA = has_next ? (const char*)g.A + nxt.offA : cA; const char* nB = has_next ? (const char*)g.Bt + nxt.offB : cB;
;         for (int t = 0; t < nt; t += 2) {
;             const bool last = (t == nt - 2);
;             const char* a1 = cA + (size_t)(t + 1) * kstep;
;             const char* a2 = last ? nA : cA + (size_t)(t + 2) * kstep; const char* b2 = last ? nB : cB + (size_t)(t + 2) * kstep;
;             const char* a3 = a2 + kstep; const char* b3 = b2 + kstep;
;     ...
; #pragma unroll
;         for (int a = 0; a < 2; ++a)
; #pragma unroll
;             for (int b = 0; b < 2; ++b)
; #pragma unroll
;                 for (int m = 0; m < 4; ++m)
; #pragma unroll
;                     for (int n = 0; n < 2; ++n) acc[a][b][m][n] = (f32x4){0.f, 0.f, 0.f, 0.f};
.LBB0_296:
	s_add_u32 s76, s66, s50
	s_addc_u32 s77, s67, s51
	v_readlane_b32 s22, v250, 44
	s_add_u32 s34, s73, s0
	v_readlane_b32 s23, v250, 45
	s_addc_u32 s35, s74, s1
	s_andn2_b64 vcc, exec, s[22:23]
	s_cbranch_vccnz .Lzc_8429
	s_and_b64 s[38:39], s[36:37], exec
	s_mov_b32 s22, s73
	s_cselect_b32 s43, s77, s9
	s_cselect_b32 s73, s76, s8
	s_cselect_b32 s82, s35, s21
	s_cselect_b32 s83, s34, s20
	s_add_u32 s84, s20, 0x100
	v_mov_b32_e32 v2, 0
	s_mov_b32 vcc_lo, s75
	s_mov_b32 s23, s74
	s_addc_u32 s85, s21, 0
	s_mov_b32 s38, 0
	s_waitcnt lgkmcnt(0)
	v_mov_b32_e32 v3, v2
	v_mov_b32_e32 v4, v2
	v_mov_b32_e32 v5, v2
	v_mov_b32_e32 v6, v2
	v_mov_b32_e32 v7, v2
	v_mov_b32_e32 v8, v2
	v_mov_b32_e32 v9, v2
	v_mov_b32_e32 v10, v2
	v_mov_b32_e32 v11, v2
	v_mov_b32_e32 v12, v2
	v_mov_b32_e32 v13, v2
	v_mov_b32_e32 v14, v2
	v_mov_b32_e32 v15, v2
	v_mov_b32_e32 v16, v2
	v_mov_b32_e32 v17, v2
	v_mov_b32_e32 v22, v2
	v_mov_b32_e32 v23, v2
	v_mov_b32_e32 v24, v2
	v_mov_b32_e32 v25, v2
	v_mov_b32_e32 v30, v2
	v_mov_b32_e32 v31, v2
	v_mov_b32_e32 v32, v2
	v_mov_b32_e32 v33, v2
	v_mov_b32_e32 v38, v2
	v_mov_b32_e32 v39, v2
	v_mov_b32_e32 v40, v2
	v_mov_b32_e32 v41, v2
	v_mov_b32_e32 v46, v2
	v_mov_b32_e32 v47, v2
	v_mov_b32_e32 v48, v2
	v_mov_b32_e32 v49, v2
	v_mov_b32_e32 v18, v2
	v_mov_b32_e32 v19, v2
	v_mov_b32_e32 v20, v2
	v_mov_b32_e32 v21, v2
	v_mov_b32_e32 v26, v2
	v_mov_b32_e32 v27, v2
	v_mov_b32_e32 v28, v2
	v_mov_b32_e32 v29, v2
	v_mov_b32_e32 v34, v2
	v_mov_b32_e32 v35, v2
	v_mov_b32_e32 v36, v2
	v_mov_b32_e32 v37, v2
	v_mov_b32_e32 v42, v2
	v_mov_b32_e32 v43, v2
	v_mov_b32_e32 v44, v2
	v_mov_b32_e32 v45, v2
	v_mov_b32_e32 v50, v2
	v_mov_b32_e32 v51, v2
	v_mov_b32_e32 v52, v2
	v_mov_b32_e32 v53, v2
	v_mov_b32_e32 v54, v2
	v_mov_b32_e32 v55, v2
	v_mov_b32_e32 v56, v2
	v_mov_b32_e32 v57, v2
	v_mov_b32_e32 v58, v2
	v_mov_b32_e32 v59, v2
	v_mov_b32_e32 v60, v2
	v_mov_b32_e32 v61, v2
	v_mov_b32_e32 v62, v2
	v_mov_b32_e32 v63, v2
	v_mov_b32_e32 v64, v2
	v_mov_b32_e32 v65, v2
	v_mov_b32_e32 v66, v2
	v_mov_b32_e32 v67, v2
	v_mov_b32_e32 v68, v2
	v_mov_b32_e32 v69, v2
	v_mov_b32_e32 v70, v2
	v_mov_b32_e32 v71, v2
	v_mov_b32_e32 v72, v2
	v_mov_b32_e32 v73, v2
	v_mov_b32_e32 v74, v2
	v_mov_b32_e32 v75, v2
	v_mov_b32_e32 v76, v2
	v_mov_b32_e32 v77, v2
	v_mov_b32_e32 v78, v2
	v_mov_b32_e32 v79, v2
	v_mov_b32_e32 v80, v2
	v_mov_b32_e32 v81, v2
	v_mov_b32_e32 v86, v2
	v_mov_b32_e32 v87, v2
	v_mov_b32_e32 v88, v2
	v_mov_b32_e32 v89, v2
	v_mov_b32_e32 v94, v2
	v_mov_b32_e32 v95, v2
	v_mov_b32_e32 v96, v2
	v_mov_b32_e32 v97, v2
	v_mov_b32_e32 v102, v2
	v_mov_b32_e32 v103, v2
	v_mov_b32_e32 v104, v2
	v_mov_b32_e32 v105, v2
	v_mov_b32_e32 v110, v2
	v_mov_b32_e32 v111, v2
	v_mov_b32_e32 v112, v2
	v_mov_b32_e32 v113, v2
	v_mov_b32_e32 v82, v2
	v_mov_b32_e32 v83, v2
	v_mov_b32_e32 v84, v2
	v_mov_b32_e32 v85, v2
	v_mov_b32_e32 v90, v2
	v_mov_b32_e32 v91, v2
	v_mov_b32_e32 v92, v2
	v_mov_b32_e32 v93, v2
	v_mov_b32_e32 v98, v2
	v_mov_b32_e32 v99, v2
	v_mov_b32_e32 v100, v2
	v_mov_b32_e32 v101, v2
	v_mov_b32_e32 v106, v2
	v_mov_b32_e32 v107, v2
	v_mov_b32_e32 v108, v2
	v_mov_b32_e32 v109, v2
	v_mov_b32_e32 v114, v2
	v_mov_b32_e32 v115, v2
	v_mov_b32_e32 v116, v2
	v_mov_b32_e32 v117, v2
	v_mov_b32_e32 v118, v2
	v_mov_b32_e32 v119, v2
	v_mov_b32_e32 v120, v2
	v_mov_b32_e32 v121, v2
	v_mov_b32_e32 v122, v2
	v_mov_b32_e32 v123, v2
	v_mov_b32_e32 v124, v2
	v_mov_b32_e32 v125, v2
	v_mov_b32_e32 v126, v2
	v_mov_b32_e32 v127, v2
	v_mov_b32_e32 v128, v2
	v_mov_b32_e32 v129, v2
	v_readfirstlane_b32 s96, v193
	s_lshr_b32 s96, s96, 8
	s_cmp_eq_u32 s96, 0
	s_cbranch_scc0 .Lnp_298
	s_setprio 1

;     __device__ bool next(int i, Unit& u) const { const int L = i * G + c; if (L >= 512) return false; u.pm = 0; u.pn = L; u.offA = 0; u.offB = (size_t)L * 256 * 256 * 2; return true; }
; template <class Epi, class Sched>
; __device__ __forceinline__ void gemm_phase(LAS unsigned char* lds, const Gemm g, const Sched& S, const Epi& E) {
;     ...
;         const bool has_next = S.next(ui + 1, nxt);
;         const char* nA = has_next ? (const char*)g.A + nxt.offA : cA; const char* nB = has_next ? (const char*)g.Bt + nxt.offB : cB;
;         for (int t = 0; t < nt; t += 2) {
;             const bool last = (t == nt - 2);
;             const char* a1 = cA + (size_t)(t + 1) * kstep;
;             const char* a2 = last ? nA : cA + (size_t)(t + 2) * kstep; const char* b2 = last ? nB : cB + (size_t)(t + 2) * kstep;
;             const char* a3 = a2 + kstep; const char* b3 = b2 + kstep;
;     ...
; #pragma unroll
;         for (int a = 0; a < 2; ++a)
; #pragma unroll
;             for (int b = 0; b < 2; ++b)
; #pragma unroll
;                 for (int m = 0; m < 4; ++m)
; #pragma unroll
;                     for (int n = 0; n < 2; ++n) acc[a][b][m][n] = (f32x4){0.f, 0.f, 0.f, 0.f};
.LBB0_483:
	s_add_u32 s76, s2, s50
	s_addc_u32 s77, s3, s51
	v_readlane_b32 s8, v254, 4
	v_readlane_b32 s9, v254, 5
	s_add_u32 s8, s8, s36
	s_addc_u32 s9, s9, s37
	s_andn2_b64 vcc, exec, s[34:35]
	s_cbranch_vccnz .Lzc_11212
	s_and_b64 s[42:43], s[20:21], exec
	s_cselect_b32 s47, s77, s39
	s_cselect_b32 s49, s76, s38
	s_cselect_b32 s73, s9, s41
	s_cselect_b32 s82, s8, s40
	s_add_u32 s38, s38, 0x40080
	s_addc_u32 s39, s39, 0
	s_add_u32 s83, s40, 0x100
	v_mov_b32_e32 v6, 0
	s_addc_u32 s84, s41, 0
	s_mov_b32 s40, 0
	v_mov_b32_e32 v7, v6
	v_mov_b32_e32 v8, v6
	v_mov_b32_e32 v9, v6
	v_mov_b32_e32 v14, v6
	v_mov_b32_e32 v15, v6
	v_mov_b32_e32 v16, v6
	v_mov_b32_e32 v17, v6
	v_mov_b32_e32 v22, v6
	v_mov_b32_e32 v23, v6
	v_mov_b32_e32 v24, v6
	v_mov_b32_e32 v25, v6
	v_mov_b32_e32 v26, v6
	v_mov_b32_e32 v27, v6
	v_mov_b32_e32 v28, v6
	v_mov_b32_e32 v29, v6
	v_mov_b32_e32 v38, v6
	v_mov_b32_e32 v39, v6
	v_mov_b32_e32 v40, v6
	v_mov_b32_e32 v41, v6
	v_mov_b32_e32 v42, v6
	v_mov_b32_e32 v43, v6
	v_mov_b32_e32 v44, v6
	v_mov_b32_e32 v45, v6
	v_mov_b32_e32 v54, v6
	v_mov_b32_e32 v55, v6
	v_mov_b32_e32 v56, v6
	v_mov_b32_e32 v57, v6
	v_mov_b32_e32 v58, v6
	v_mov_b32_e32 v59, v6
	v_mov_b32_e32 v60, v6
	v_mov_b32_e32 v61, v6
	v_mov_b32_e32 v2, v6
	v_mov_b32_e32 v3, v6
	v_mov_b32_e32 v4, v6
	v_mov_b32_e32 v5, v6
	v_mov_b32_e32 v10, v6
	v_mov_b32_e32 v11, v6
	v_mov_b32_e32 v12, v6
	v_mov_b32_e32 v13, v6
	v_mov_b32_e32 v18, v6
	v_mov_b32_e32 v19, v6
	v_mov_b32_e32 v20, v6
	v_mov_b32_e32 v21, v6
	v_mov_b32_e32 v30, v6
	v_mov_b32_e32 v31, v6
	v_mov_b32_e32 v32, v6
	v_mov_b32_e32 v33, v6
	v_mov_b32_e32 v34, v6
	v_mov_b32_e32 v35, v6
	v_mov_b32_e32 v36, v6
	v_mov_b32_e32 v37, v6
	v_mov_b32_e32 v46, v6
	v_mov_b32_e32 v47, v6
	v_mov_b32_e32 v48, v6
	v_mov_b32_e32 v49, v6
	v_mov_b32_e32 v50, v6
	v_mov_b32_e32 v51, v6
	v_mov_b32_e32 v52, v6
	v_mov_b32_e32 v53, v6
	v_mov_b32_e32 v62, v6
	v_mov_b32_e32 v63, v6
	v_mov_b32_e32 v64, v6
	v_mov_b32_e32 v65, v6
	v_mov_b32_e32 v70, v6
	v_mov_b32_e32 v71, v6
	v_mov_b32_e32 v72, v6
	v_mov_b32_e32 v73, v6
	v_mov_b32_e32 v74, v6
	v_mov_b32_e32 v75, v6
	v_mov_b32_e32 v76, v6
	v_mov_b32_e32 v77, v6
	v_mov_b32_e32 v86, v6
	v_mov_b32_e32 v87, v6
	v_mov_b32_e32 v88, v6
	v_mov_b32_e32 v89, v6
	v_mov_b32_e32 v90, v6
	v_mov_b32_e32 v91, v6
	v_mov_b32_e32 v92, v6
	v_mov_b32_e32 v93, v6
	v_mov_b32_e32 v102, v6
	v_mov_b32_e32 v103, v6
	v_mov_b32_e32 v104, v6
	v_mov_b32_e32 v105, v6
	v_mov_b32_e32 v106, v6
	v_mov_b32_e32 v107, v6
	v_mov_b32_e32 v108, v6
	v_mov_b32_e32 v109, v6
	v_mov_b32_e32 v118, v6
	v_mov_b32_e32 v119, v6
	v_mov_b32_e32 v120, v6
	v_mov_b32_e32 v121, v6
	v_mov_b32_e32 v126, v6
	v_mov_b32_e32 v127, v6
	v_mov_b32_e32 v128, v6
	v_mov_b32_e32 v129, v6
	v_mov_b32_e32 v66, v6
	v_mov_b32_e32 v67, v6
	v_mov_b32_e32 v68, v6
	v_mov_b32_e32 v69, v6
	v_mov_b32_e32 v78, v6
	v_mov_b32_e32 v79, v6
	v_mov_b32_e32 v80, v6
	v_mov_b32_e32 v81, v6
	v_mov_b32_e32 v82, v6
	v_mov_b32_e32 v83, v6
	v_mov_b32_e32 v84, v6
	v_mov_b32_e32 v85, v6
	v_mov_b32_e32 v94, v6
	v_mov_b32_e32 v95, v6
	v_mov_b32_e32 v96, v6
	v_mov_b32_e32 v97, v6
	v_mov_b32_e32 v98, v6
	v_mov_b32_e32 v99, v6
	v_mov_b32_e32 v100, v6
	v_mov_b32_e32 v101, v6
	v_mov_b32_e32 v110, v6
	v_mov_b32_e32 v111, v6
	v_mov_b32_e32 v112, v6
	v_mov_b32_e32 v113, v6
	v_mov_b32_e32 v114, v6
	v_mov_b32_e32 v115, v6
	v_mov_b32_e32 v116, v6
	v_mov_b32_e32 v117, v6
	v_mov_b32_e32 v122, v6
	v_mov_b32_e32 v123, v6
	v_mov_b32_e32 v124, v6
	v_mov_b32_e32 v125, v6
	v_readfirstlane_b32 s85, v193
	s_lshr_b32 s85, s85, 8
	s_cmp_eq_u32 s85, 0
	s_cbranch_scc0 .Lnp_485
	s_setprio 1

;     __device__ bool next(int i, Unit& u) const { const int L = i * G + c; if (L >= 512) return false; u.pm = 0; u.pn = L; u.offA = 0; u.offB = (size_t)L * 256 * 256 * 2; return true; }
; template <class Epi, class Sched>
; __device__ __forceinline__ void gemm_phase(LAS unsigned char* lds, const Gemm g, const Sched& S, const Epi& E) {
;     ...
;         const bool has_next = S.next(ui + 1, nxt);
;         const char* nA = has_next ? (const char*)g.A + nxt.offA : cA; const char* nB = has_next ? (const char*)g.Bt + nxt.offB : cB;
;         for (int t = 0; t < nt; t += 2) {
;             const bool last = (t == nt - 2);
;             const char* a1 = cA + (size_t)(t + 1) * kstep;
;             const char* a2 = last ? nA : cA + (size_t)(t + 2) * kstep; const char* b2 = last ? nB : cB + (size_t)(t + 2) * kstep;
;             const char* a3 = a2 + kstep; const char* b3 = b2 + kstep;
;     ...
; #pragma unroll
;         for (int a = 0; a < 2; ++a)
; #pragma unroll
;             for (int b = 0; b < 2; ++b)
; #pragma unroll
;                 for (int m = 0; m < 4; ++m)
; #pragma unroll
;                     for (int n = 0; n < 2; ++n) acc[a][b][m][n] = (f32x4){0.f, 0.f, 0.f, 0.f};
.LBB0_534:
	v_readlane_b32 s22, v251, 29
	v_readlane_b32 s23, v251, 30
	s_add_u32 s40, s22, s34
	s_addc_u32 s41, s23, s35
	s_add_u32 s42, s2, s36
	s_addc_u32 s43, s3, s37
	s_andn2_b64 vcc, exec, s[8:9]
	s_cbranch_vccnz .Lzc_13474
	s_and_b64 s[76:77], s[38:39], exec
	s_cselect_b32 s73, s41, s45
	s_cselect_b32 s76, s40, s44
	s_cselect_b32 s77, s43, s47
	s_cselect_b32 s78, s42, s46
	s_add_u32 s44, s44, 0x40080
	s_addc_u32 s45, s45, 0
	s_add_u32 s80, s46, 0x100
	v_mov_b32_e32 v2, 0
	s_addc_u32 s82, s47, 0
	s_mov_b32 s46, 0
	v_mov_b32_e32 v3, v2
	v_mov_b32_e32 v4, v2
	v_mov_b32_e32 v5, v2
	v_mov_b32_e32 v6, v2
	v_mov_b32_e32 v7, v2
	v_mov_b32_e32 v8, v2
	v_mov_b32_e32 v9, v2
	v_mov_b32_e32 v18, v2
	v_mov_b32_e32 v19, v2
	v_mov_b32_e32 v20, v2
	v_mov_b32_e32 v21, v2
	v_mov_b32_e32 v22, v2
	v_mov_b32_e32 v23, v2
	v_mov_b32_e32 v24, v2
	v_mov_b32_e32 v25, v2
	v_mov_b32_e32 v34, v2
	v_mov_b32_e32 v35, v2
	v_mov_b32_e32 v36, v2
	v_mov_b32_e32 v37, v2
	v_mov_b32_e32 v38, v2
	v_mov_b32_e32 v39, v2
	v_mov_b32_e32 v40, v2
	v_mov_b32_e32 v41, v2
	v_mov_b32_e32 v50, v2
	v_mov_b32_e32 v51, v2
	v_mov_b32_e32 v52, v2
	v_mov_b32_e32 v53, v2
	v_mov_b32_e32 v54, v2
	v_mov_b32_e32 v55, v2
	v_mov_b32_e32 v56, v2
	v_mov_b32_e32 v57, v2
	v_mov_b32_e32 v10, v2
	v_mov_b32_e32 v11, v2
	v_mov_b32_e32 v12, v2
	v_mov_b32_e32 v13, v2
	v_mov_b32_e32 v14, v2
	v_mov_b32_e32 v15, v2
	v_mov_b32_e32 v16, v2
	v_mov_b32_e32 v17, v2
	v_mov_b32_e32 v26, v2
	v_mov_b32_e32 v27, v2
	v_mov_b32_e32 v28, v2
	v_mov_b32_e32 v29, v2
	v_mov_b32_e32 v30, v2
	v_mov_b32_e32 v31, v2
	v_mov_b32_e32 v32, v2
	v_mov_b32_e32 v33, v2
	v_mov_b32_e32 v42, v2
	v_mov_b32_e32 v43, v2
	v_mov_b32_e32 v44, v2
	v_mov_b32_e32 v45, v2
	v_mov_b32_e32 v46, v2
	v_mov_b32_e32 v47, v2
	v_mov_b32_e32 v48, v2
	v_mov_b32_e32 v49, v2
	v_mov_b32_e32 v58, v2
	v_mov_b32_e32 v59, v2
	v_mov_b32_e32 v60, v2
	v_mov_b32_e32 v61, v2
	v_mov_b32_e32 v62, v2
	v_mov_b32_e32 v63, v2
	v_mov_b32_e32 v64, v2
	v_mov_b32_e32 v65, v2
	v_mov_b32_e32 v66, v2
	v_mov_b32_e32 v67, v2
	v_mov_b32_e32 v68, v2
	v_mov_b32_e32 v69, v2
	v_mov_b32_e32 v70, v2
	v_mov_b32_e32 v71, v2
	v_mov_b32_e32 v72, v2
	v_mov_b32_e32 v73, v2
	v_mov_b32_e32 v82, v2
	v_mov_b32_e32 v83, v2
	v_mov_b32_e32 v84, v2
	v_mov_b32_e32 v85, v2
	v_mov_b32_e32 v86, v2
	v_mov_b32_e32 v87, v2
	v_mov_b32_e32 v88, v2
	v_mov_b32_e32 v89, v2
	v_mov_b32_e32 v98, v2
	v_mov_b32_e32 v99, v2
	v_mov_b32_e32 v100, v2
	v_mov_b32_e32 v101, v2
	v_mov_b32_e32 v102, v2
	v_mov_b32_e32 v103, v2
	v_mov_b32_e32 v104, v2
	v_mov_b32_e32 v105, v2
	v_mov_b32_e32 v114, v2
	v_mov_b32_e32 v115, v2
	v_mov_b32_e32 v116, v2
	v_mov_b32_e32 v117, v2
	v_mov_b32_e32 v118, v2
	v_mov_b32_e32 v119, v2
	v_mov_b32_e32 v120, v2
	v_mov_b32_e32 v121, v2
	v_mov_b32_e32 v74, v2
	v_mov_b32_e32 v75, v2
	v_mov_b32_e32 v76, v2
	v_mov_b32_e32 v77, v2
	v_mov_b32_e32 v78, v2
	v_mov_b32_e32 v79, v2
	v_mov_b32_e32 v80, v2
	v_mov_b32_e32 v81, v2
	v_mov_b32_e32 v90, v2
	v_mov_b32_e32 v91, v2
	v_mov_b32_e32 v92, v2
	v_mov_b32_e32 v93, v2
	v_mov_b32_e32 v94, v2
	v_mov_b32_e32 v95, v2
	v_mov_b32_e32 v96, v2
	v_mov_b32_e32 v97, v2
	v_mov_b32_e32 v106, v2
	v_mov_b32_e32 v107, v2
	v_mov_b32_e32 v108, v2
	v_mov_b32_e32 v109, v2
	v_mov_b32_e32 v110, v2
	v_mov_b32_e32 v111, v2
	v_mov_b32_e32 v112, v2
	v_mov_b32_e32 v113, v2
	v_mov_b32_e32 v126, v2
	v_mov_b32_e32 v127, v2
	v_mov_b32_e32 v128, v2
	v_mov_b32_e32 v129, v2
	v_mov_b32_e32 v122, v2
	v_mov_b32_e32 v123, v2
	v_mov_b32_e32 v124, v2
	v_mov_b32_e32 v125, v2
	s_mov_b64 s[22:23], 0x800
	s_mov_b64 vcc, 0x880
	v_readfirstlane_b32 s83, v193
	s_lshr_b32 s83, s83, 8
	s_cmp_eq_u32 s83, 0
	s_cbranch_scc0 .Lnp_536
	s_setprio 1

;     __device__ bool next(int i, Unit& u) const { const int L = i * G + c; if (L >= 512) return false; u.pm = 0; u.pn = L; u.offA = 0; u.offB = (size_t)L * 256 * 256 * 2; return true; }
; template <class Epi, class Sched>
; __device__ __forceinline__ void gemm_phase(LAS unsigned char* lds, const Gemm g, const Sched& S, const Epi& E) {
;     ...
;         const bool has_next = S.next(ui + 1, nxt);
;         const char* nA = has_next ? (const char*)g.A + nxt.offA : cA; const char* nB = has_next ? (const char*)g.Bt + nxt.offB : cB;
;         for (int t = 0; t < nt; t += 2) {
;             const bool last = (t == nt - 2);
;             const char* a1 = cA + (size_t)(t + 1) * kstep;
;             const char* a2 = last ? nA : cA + (size_t)(t + 2) * kstep; const char* b2 = last ? nB : cB + (size_t)(t + 2) * kstep;
;             const char* a3 = a2 + kstep; const char* b3 = b2 + kstep;
;     ...
; #pragma unroll
;         for (int a = 0; a < 2; ++a)
; #pragma unroll
;             for (int b = 0; b < 2; ++b)
; #pragma unroll
;                 for (int m = 0; m < 4; ++m)
; #pragma unroll
;                     for (int n = 0; n < 2; ++n) acc[a][b][m][n] = (f32x4){0.f, 0.f, 0.f, 0.f};
.LBB0_635:
	s_add_u32 s38, s68, s36
	s_addc_u32 s39, s69, s37
	s_andn2_b64 vcc, exec, s[20:21]
	s_cbranch_vccnz .Lzc_17144
	s_and_b64 s[0:1], s[40:41], exec
	s_cselect_b32 s73, s39, s43
	s_cselect_b32 s76, s38, s42
	s_add_u32 s77, s42, 0x100
	v_mov_b32_e32 v2, 0
	s_addc_u32 s78, s43, 0
	s_mov_b32 s46, 0
	s_mov_b64 s[42:43], 0
	v_mov_b32_e32 v3, v2
	v_mov_b32_e32 v4, v2
	v_mov_b32_e32 v5, v2
	v_mov_b32_e32 v10, v2
	v_mov_b32_e32 v11, v2
	v_mov_b32_e32 v12, v2
	v_mov_b32_e32 v13, v2
	v_mov_b32_e32 v34, v2
	v_mov_b32_e32 v35, v2
	v_mov_b32_e32 v36, v2
	v_mov_b32_e32 v37, v2
	v_mov_b32_e32 v42, v2
	v_mov_b32_e32 v43, v2
	v_mov_b32_e32 v44, v2
	v_mov_b32_e32 v45, v2
	v_mov_b32_e32 v66, v2
	v_mov_b32_e32 v67, v2
	v_mov_b32_e32 v68, v2
	v_mov_b32_e32 v69, v2
	v_mov_b32_e32 v74, v2
	v_mov_b32_e32 v75, v2
	v_mov_b32_e32 v76, v2
	v_mov_b32_e32 v77, v2
	v_mov_b32_e32 v98, v2
	v_mov_b32_e32 v99, v2
	v_mov_b32_e32 v100, v2
	v_mov_b32_e32 v101, v2
	v_mov_b32_e32 v106, v2
	v_mov_b32_e32 v107, v2
	v_mov_b32_e32 v108, v2
	v_mov_b32_e32 v109, v2
	v_mov_b32_e32 v18, v2
	v_mov_b32_e32 v19, v2
	v_mov_b32_e32 v20, v2
	v_mov_b32_e32 v21, v2
	v_mov_b32_e32 v26, v2
	v_mov_b32_e32 v27, v2
	v_mov_b32_e32 v28, v2
	v_mov_b32_e32 v29, v2
	v_mov_b32_e32 v50, v2
	v_mov_b32_e32 v51, v2
	v_mov_b32_e32 v52, v2
	v_mov_b32_e32 v53, v2
	v_mov_b32_e32 v58, v2
	v_mov_b32_e32 v59, v2
	v_mov_b32_e32 v60, v2
	v_mov_b32_e32 v61, v2
	v_mov_b32_e32 v82, v2
	v_mov_b32_e32 v83, v2
	v_mov_b32_e32 v84, v2
	v_mov_b32_e32 v85, v2
	v_mov_b32_e32 v90, v2
	v_mov_b32_e32 v91, v2
	v_mov_b32_e32 v92, v2
	v_mov_b32_e32 v93, v2
	v_mov_b32_e32 v114, v2
	v_mov_b32_e32 v115, v2
	v_mov_b32_e32 v116, v2
	v_mov_b32_e32 v117, v2
	v_mov_b32_e32 v122, v2
	v_mov_b32_e32 v123, v2
	v_mov_b32_e32 v124, v2
	v_mov_b32_e32 v125, v2
	v_mov_b32_e32 v6, v2
	v_mov_b32_e32 v7, v2
	v_mov_b32_e32 v8, v2
	v_mov_b32_e32 v9, v2
	v_mov_b32_e32 v14, v2
	v_mov_b32_e32 v15, v2
	v_mov_b32_e32 v16, v2
	v_mov_b32_e32 v17, v2
	v_mov_b32_e32 v38, v2
	v_mov_b32_e32 v39, v2
	v_mov_b32_e32 v40, v2
	v_mov_b32_e32 v41, v2
	v_mov_b32_e32 v46, v2
	v_mov_b32_e32 v47, v2
	v_mov_b32_e32 v48, v2
	v_mov_b32_e32 v49, v2
	v_mov_b32_e32 v70, v2
	v_mov_b32_e32 v71, v2
	v_mov_b32_e32 v72, v2
	v_mov_b32_e32 v73, v2
	v_mov_b32_e32 v78, v2
	v_mov_b32_e32 v79, v2
	v_mov_b32_e32 v80, v2
	v_mov_b32_e32 v81, v2
	v_mov_b32_e32 v102, v2
	v_mov_b32_e32 v103, v2
	v_mov_b32_e32 v104, v2
	v_mov_b32_e32 v105, v2
	v_mov_b32_e32 v110, v2
	v_mov_b32_e32 v111, v2
	v_mov_b32_e32 v112, v2
	v_mov_b32_e32 v113, v2
	v_mov_b32_e32 v22, v2
	v_mov_b32_e32 v23, v2
	v_mov_b32_e32 v24, v2
	v_mov_b32_e32 v25, v2
	v_mov_b32_e32 v30, v2
	v_mov_b32_e32 v31, v2
	v_mov_b32_e32 v32, v2
	v_mov_b32_e32 v33, v2
	v_mov_b32_e32 v54, v2
	v_mov_b32_e32 v55, v2
	v_mov_b32_e32 v56, v2
	v_mov_b32_e32 v57, v2
	v_mov_b32_e32 v62, v2
	v_mov_b32_e32 v63, v2
	v_mov_b32_e32 v64, v2
	v_mov_b32_e32 v65, v2
	v_mov_b32_e32 v86, v2
	v_mov_b32_e32 v87, v2
	v_mov_b32_e32 v88, v2
	v_mov_b32_e32 v89, v2
	v_mov_b32_e32 v94, v2
	v_mov_b32_e32 v95, v2
	v_mov_b32_e32 v96, v2
	v_mov_b32_e32 v97, v2
	v_mov_b32_e32 v118, v2
	v_mov_b32_e32 v119, v2
	v_mov_b32_e32 v120, v2
	v_mov_b32_e32 v121, v2
	v_mov_b32_e32 v126, v2
	v_mov_b32_e32 v127, v2
	v_mov_b32_e32 v128, v2
	v_mov_b32_e32 v129, v2
	v_readfirstlane_b32 s0, v193
	s_lshr_b32 s0, s0, 8
	s_cmp_eq_u32 s0, 0
	s_cbranch_scc0 .Lnp_637
	s_setprio 1

;     __device__ bool next(int i, Unit& u) const { const int L = i * G + c; if (L >= 512) return false; u.pm = 0; u.pn = L; u.offA = 0; u.offB = (size_t)L * 256 * 256 * 2; return true; }
; template <class Epi, class Sched>
; __device__ __forceinline__ void gemm_phase(LAS unsigned char* lds, const Gemm g, const Sched& S, const Epi& E) {
;     ...
;         const bool has_next = S.next(ui + 1, nxt);
;         const char* nA = has_next ? (const char*)g.A + nxt.offA : cA; const char* nB = has_next ? (const char*)g.Bt + nxt.offB : cB;
;         for (int t = 0; t < nt; t += 2) {
;             const bool last = (t == nt - 2);
;             const char* a1 = cA + (size_t)(t + 1) * kstep;
;             const char* a2 = last ? nA : cA + (size_t)(t + 2) * kstep; const char* b2 = last ? nB : cB + (size_t)(t + 2) * kstep;
;             const char* a3 = a2 + kstep; const char* b3 = b2 + kstep;
;     ...
; #pragma unroll
;         for (int a = 0; a < 2; ++a)
; #pragma unroll
;             for (int b = 0; b < 2; ++b)
; #pragma unroll
;                 for (int m = 0; m < 4; ++m)
; #pragma unroll
;                     for (int n = 0; n < 2; ++n) acc[a][b][m][n] = (f32x4){0.f, 0.f, 0.f, 0.f};
.LBB0_658:
	s_add_u32 s8, s2, s50
	s_addc_u32 s9, s3, s51
	v_readlane_b32 s0, v254, 4
	v_readlane_b32 s1, v254, 5
	s_add_u32 s20, s0, s76
	s_addc_u32 s21, s1, s77
	s_andn2_b64 vcc, exec, s[34:35]
	s_cbranch_vccnz .Lzc_19087
	s_and_b64 s[0:1], s[38:39], exec
	s_cselect_b32 s47, s9, s37
	s_cselect_b32 s49, s8, s36
	s_cselect_b32 s83, s21, s41
	s_cselect_b32 vcc_lo, s20, s40
	s_add_u32 s36, s36, 0x40080
	s_addc_u32 s37, s37, 0
	s_add_u32 vcc_hi, s40, 0x100
	v_mov_b32_e32 v6, 0
	s_addc_u32 s96, s41, 0
	s_mov_b32 s40, 0
	v_mov_b32_e32 v7, v6
	v_mov_b32_e32 v8, v6
	v_mov_b32_e32 v9, v6
	v_mov_b32_e32 v14, v6
	v_mov_b32_e32 v15, v6
	v_mov_b32_e32 v16, v6
	v_mov_b32_e32 v17, v6
	v_mov_b32_e32 v22, v6
	v_mov_b32_e32 v23, v6
	v_mov_b32_e32 v24, v6
	v_mov_b32_e32 v25, v6
	v_mov_b32_e32 v26, v6
	v_mov_b32_e32 v27, v6
	v_mov_b32_e32 v28, v6
	v_mov_b32_e32 v29, v6
	v_mov_b32_e32 v38, v6
	v_mov_b32_e32 v39, v6
	v_mov_b32_e32 v40, v6
	v_mov_b32_e32 v41, v6
	v_mov_b32_e32 v42, v6
	v_mov_b32_e32 v43, v6
	v_mov_b32_e32 v44, v6
	v_mov_b32_e32 v45, v6
	v_mov_b32_e32 v54, v6
	v_mov_b32_e32 v55, v6
	v_mov_b32_e32 v56, v6
	v_mov_b32_e32 v57, v6
	v_mov_b32_e32 v58, v6
	v_mov_b32_e32 v59, v6
	v_mov_b32_e32 v60, v6
	v_mov_b32_e32 v61, v6
	v_mov_b32_e32 v2, v6
	v_mov_b32_e32 v3, v6
	v_mov_b32_e32 v4, v6
	v_mov_b32_e32 v5, v6
	v_mov_b32_e32 v10, v6
	v_mov_b32_e32 v11, v6
	v_mov_b32_e32 v12, v6
	v_mov_b32_e32 v13, v6
	v_mov_b32_e32 v18, v6
	v_mov_b32_e32 v19, v6
	v_mov_b32_e32 v20, v6
	v_mov_b32_e32 v21, v6
	v_mov_b32_e32 v30, v6
	v_mov_b32_e32 v31, v6
	v_mov_b32_e32 v32, v6
	v_mov_b32_e32 v33, v6
	v_mov_b32_e32 v34, v6
	v_mov_b32_e32 v35, v6
	v_mov_b32_e32 v36, v6
	v_mov_b32_e32 v37, v6
	v_mov_b32_e32 v46, v6
	v_mov_b32_e32 v47, v6
	v_mov_b32_e32 v48, v6
	v_mov_b32_e32 v49, v6
	v_mov_b32_e32 v50, v6
	v_mov_b32_e32 v51, v6
	v_mov_b32_e32 v52, v6
	v_mov_b32_e32 v53, v6
	v_mov_b32_e32 v62, v6
	v_mov_b32_e32 v63, v6
	v_mov_b32_e32 v64, v6
	v_mov_b32_e32 v65, v6
	v_mov_b32_e32 v70, v6
	v_mov_b32_e32 v71, v6
	v_mov_b32_e32 v72, v6
	v_mov_b32_e32 v73, v6
	v_mov_b32_e32 v74, v6
	v_mov_b32_e32 v75, v6
	v_mov_b32_e32 v76, v6
	v_mov_b32_e32 v77, v6
	v_mov_b32_e32 v86, v6
	v_mov_b32_e32 v87, v6
	v_mov_b32_e32 v88, v6
	v_mov_b32_e32 v89, v6
	v_mov_b32_e32 v90, v6
	v_mov_b32_e32 v91, v6
	v_mov_b32_e32 v92, v6
	v_mov_b32_e32 v93, v6
	v_mov_b32_e32 v102, v6
	v_mov_b32_e32 v103, v6
	v_mov_b32_e32 v104, v6
	v_mov_b32_e32 v105, v6
	v_mov_b32_e32 v106, v6
	v_mov_b32_e32 v107, v6
	v_mov_b32_e32 v108, v6
	v_mov_b32_e32 v109, v6
	v_mov_b32_e32 v118, v6
	v_mov_b32_e32 v119, v6
	v_mov_b32_e32 v120, v6
	v_mov_b32_e32 v121, v6
	v_mov_b32_e32 v126, v6
	v_mov_b32_e32 v127, v6
	v_mov_b32_e32 v128, v6
	v_mov_b32_e32 v129, v6
	v_mov_b32_e32 v66, v6
	v_mov_b32_e32 v67, v6
	v_mov_b32_e32 v68, v6
	v_mov_b32_e32 v69, v6
	v_mov_b32_e32 v78, v6
	v_mov_b32_e32 v79, v6
	v_mov_b32_e32 v80, v6
	v_mov_b32_e32 v81, v6
	v_mov_b32_e32 v82, v6
	v_mov_b32_e32 v83, v6
	v_mov_b32_e32 v84, v6
	v_mov_b32_e32 v85, v6
	v_mov_b32_e32 v94, v6
	v_mov_b32_e32 v95, v6
	v_mov_b32_e32 v96, v6
	v_mov_b32_e32 v97, v6
	v_mov_b32_e32 v98, v6
	v_mov_b32_e32 v99, v6
	v_mov_b32_e32 v100, v6
	v_mov_b32_e32 v101, v6
	v_mov_b32_e32 v110, v6
	v_mov_b32_e32 v111, v6
	v_mov_b32_e32 v112, v6
	v_mov_b32_e32 v113, v6
	v_mov_b32_e32 v114, v6
	v_mov_b32_e32 v115, v6
	v_mov_b32_e32 v116, v6
	v_mov_b32_e32 v117, v6
	v_mov_b32_e32 v122, v6
	v_mov_b32_e32 v123, v6
	v_mov_b32_e32 v124, v6
	v_mov_b32_e32 v125, v6
	v_readfirstlane_b32 s0, v193
	s_lshr_b32 s0, s0, 8
	s_cmp_eq_u32 s0, 0
	s_cbranch_scc0 .Lnp_660
	s_setprio 1

;     __device__ bool next(int i, Unit& u) const { const int L = i * G + c; if (L >= 512) return false; u.pm = 0; u.pn = L; u.offA = 0; u.offB = (size_t)L * 256 * 256 * 2; return true; }
; template <class Epi, class Sched>
; __device__ __forceinline__ void gemm_phase(LAS unsigned char* lds, const Gemm g, const Sched& S, const Epi& E) {
;     ...
;         const bool has_next = S.next(ui + 1, nxt);
;         const char* nA = has_next ? (const char*)g.A + nxt.offA : cA; const char* nB = has_next ? (const char*)g.Bt + nxt.offB : cB;
;         for (int t = 0; t < nt; t += 2) {
;             const bool last = (t == nt - 2);
;             const char* a1 = cA + (size_t)(t + 1) * kstep;
;             const char* a2 = last ? nA : cA + (size_t)(t + 2) * kstep; const char* b2 = last ? nB : cB + (size_t)(t + 2) * kstep;
;             const char* a3 = a2 + kstep; const char* b3 = b2 + kstep;
;     ...
; #pragma unroll
;         for (int a = 0; a < 2; ++a)
; #pragma unroll
;             for (int b = 0; b < 2; ++b)
; #pragma unroll
;                 for (int m = 0; m < 4; ++m)
; #pragma unroll
;                     for (int n = 0; n < 2; ++n) acc[a][b][m][n] = (f32x4){0.f, 0.f, 0.f, 0.f};
.LBB0_761:
	s_add_u32 s40, s54, s36
	s_addc_u32 s41, s55, s37
	s_andn2_b64 vcc, exec, s[8:9]
	s_cbranch_vccnz .Lzc_21902
	s_and_b64 s[44:45], s[38:39], exec
	s_cselect_b32 s52, s41, s43
	s_cselect_b32 s56, s40, s42
	s_add_u32 s57, s42, 0x100
	v_mov_b32_e32 v2, 0
	v_readlane_b32 s22, v250, 4
	s_addc_u32 s64, s43, 0
	s_mov_b32 s46, 0
	s_mov_b64 s[42:43], 0
	v_mov_b32_e32 v3, v2
	v_mov_b32_e32 v4, v2
	v_mov_b32_e32 v5, v2
	v_mov_b32_e32 v6, v2
	v_mov_b32_e32 v7, v2
	v_mov_b32_e32 v8, v2
	v_mov_b32_e32 v9, v2
	v_mov_b32_e32 v18, v2
	v_mov_b32_e32 v19, v2
	v_mov_b32_e32 v20, v2
	v_mov_b32_e32 v21, v2
	v_mov_b32_e32 v22, v2
	v_mov_b32_e32 v23, v2
	v_mov_b32_e32 v24, v2
	v_mov_b32_e32 v25, v2
	v_mov_b32_e32 v34, v2
	v_mov_b32_e32 v35, v2
	v_mov_b32_e32 v36, v2
	v_mov_b32_e32 v37, v2
	v_mov_b32_e32 v38, v2
	v_mov_b32_e32 v39, v2
	v_mov_b32_e32 v40, v2
	v_mov_b32_e32 v41, v2
	v_mov_b32_e32 v50, v2
	v_mov_b32_e32 v51, v2
	v_mov_b32_e32 v52, v2
	v_mov_b32_e32 v53, v2
	v_mov_b32_e32 v54, v2
	v_mov_b32_e32 v55, v2
	v_mov_b32_e32 v56, v2
	v_mov_b32_e32 v57, v2
	v_mov_b32_e32 v10, v2
	v_mov_b32_e32 v11, v2
	v_mov_b32_e32 v12, v2
	v_mov_b32_e32 v13, v2
	v_mov_b32_e32 v14, v2
	v_mov_b32_e32 v15, v2
	v_mov_b32_e32 v16, v2
	v_mov_b32_e32 v17, v2
	v_mov_b32_e32 v26, v2
	v_mov_b32_e32 v27, v2
	v_mov_b32_e32 v28, v2
	v_mov_b32_e32 v29, v2
	v_mov_b32_e32 v30, v2
	v_mov_b32_e32 v31, v2
	v_mov_b32_e32 v32, v2
	v_mov_b32_e32 v33, v2
	v_mov_b32_e32 v42, v2
	v_mov_b32_e32 v43, v2
	v_mov_b32_e32 v44, v2
	v_mov_b32_e32 v45, v2
	v_mov_b32_e32 v46, v2
	v_mov_b32_e32 v47, v2
	v_mov_b32_e32 v48, v2
	v_mov_b32_e32 v49, v2
	v_mov_b32_e32 v58, v2
	v_mov_b32_e32 v59, v2
	v_mov_b32_e32 v60, v2
	v_mov_b32_e32 v61, v2
	v_mov_b32_e32 v62, v2
	v_mov_b32_e32 v63, v2
	v_mov_b32_e32 v64, v2
	v_mov_b32_e32 v65, v2
	v_mov_b32_e32 v66, v2
	v_mov_b32_e32 v67, v2
	v_mov_b32_e32 v68, v2
	v_mov_b32_e32 v69, v2
	v_mov_b32_e32 v70, v2
	v_mov_b32_e32 v71, v2
	v_mov_b32_e32 v72, v2
	v_mov_b32_e32 v73, v2
	v_mov_b32_e32 v82, v2
	v_mov_b32_e32 v83, v2
	v_mov_b32_e32 v84, v2
	v_mov_b32_e32 v85, v2
	v_mov_b32_e32 v86, v2
	v_mov_b32_e32 v87, v2
	v_mov_b32_e32 v88, v2
	v_mov_b32_e32 v89, v2
	v_mov_b32_e32 v98, v2
	v_mov_b32_e32 v99, v2
	v_mov_b32_e32 v100, v2
	v_mov_b32_e32 v101, v2
	v_mov_b32_e32 v102, v2
	v_mov_b32_e32 v103, v2
	v_mov_b32_e32 v104, v2
	v_mov_b32_e32 v105, v2
	v_mov_b32_e32 v114, v2
	v_mov_b32_e32 v115, v2
	v_mov_b32_e32 v116, v2
	v_mov_b32_e32 v117, v2
	v_mov_b32_e32 v118, v2
	v_mov_b32_e32 v119, v2
	v_mov_b32_e32 v120, v2
	v_mov_b32_e32 v121, v2
	v_mov_b32_e32 v74, v2
	v_mov_b32_e32 v75, v2
	v_mov_b32_e32 v76, v2
	v_mov_b32_e32 v77, v2
	v_mov_b32_e32 v78, v2
	v_mov_b32_e32 v79, v2
	v_mov_b32_e32 v80, v2
	v_mov_b32_e32 v81, v2
	v_mov_b32_e32 v90, v2
	v_mov_b32_e32 v91, v2
	v_mov_b32_e32 v92, v2
	v_mov_b32_e32 v93, v2
	v_mov_b32_e32 v94, v2
	v_mov_b32_e32 v95, v2
	v_mov_b32_e32 v96, v2
	v_mov_b32_e32 v97, v2
	v_mov_b32_e32 v106, v2
	v_mov_b32_e32 v107, v2
	v_mov_b32_e32 v108, v2
	v_mov_b32_e32 v109, v2
	v_mov_b32_e32 v110, v2
	v_mov_b32_e32 v111, v2
	v_mov_b32_e32 v112, v2
	v_mov_b32_e32 v113, v2
	v_mov_b32_e32 v126, v2
	v_mov_b32_e32 v127, v2
	v_mov_b32_e32 v128, v2
	v_mov_b32_e32 v129, v2
	v_mov_b32_e32 v122, v2
	v_mov_b32_e32 v123, v2
	v_mov_b32_e32 v124, v2
	v_mov_b32_e32 v125, v2
	v_readlane_b32 s23, v250, 5
	v_readlane_b32 s78, v250, 36
	v_readfirstlane_b32 s73, v193
	s_lshr_b32 s73, s73, 8
	s_cmp_eq_u32 s73, 0
	s_cbranch_scc0 .Lnp_763
	s_setprio 1

;     __device__ bool next(int i, Unit& u) const { const int L = i * G + c; if (L >= 512) return false; u.pm = 0; u.pn = L; u.offA = 0; u.offB = (size_t)L * 256 * 256 * 2; return true; }
; template <class Epi, class Sched>
; __device__ __forceinline__ void gemm_phase(LAS unsigned char* lds, const Gemm g, const Sched& S, const Epi& E) {
;     ...
;         const bool has_next = S.next(ui + 1, nxt);
;         const char* nA = has_next ? (const char*)g.A + nxt.offA : cA; const char* nB = has_next ? (const char*)g.Bt + nxt.offB : cB;
;         for (int t = 0; t < nt; t += 2) {
;             const bool last = (t == nt - 2);
;             const char* a1 = cA + (size_t)(t + 1) * kstep;
;             const char* a2 = last ? nA : cA + (size_t)(t + 2) * kstep; const char* b2 = last ? nB : cB + (size_t)(t + 2) * kstep;
;             const char* a3 = a2 + kstep; const char* b3 = b2 + kstep;
;     ...
; #pragma unroll
;         for (int a = 0; a < 2; ++a)
; #pragma unroll
;             for (int b = 0; b < 2; ++b)
; #pragma unroll
;                 for (int m = 0; m < 4; ++m)
; #pragma unroll
;                     for (int n = 0; n < 2; ++n) acc[a][b][m][n] = (f32x4){0.f, 0.f, 0.f, 0.f};
.LBB0_910:
	s_add_u32 s46, s54, s42
	s_addc_u32 s47, s55, s43
	v_readlane_b32 s22, v254, 12
	v_readlane_b32 s23, v254, 13
	s_add_u32 s48, s22, s44
	s_addc_u32 s49, s23, s45
	s_andn2_b64 vcc, exec, s[20:21]
	s_waitcnt lgkmcnt(0)
	s_cbranch_vccnz .Lzc_25928
	s_and_b64 s[76:77], s[36:37], exec
	s_cselect_b32 s39, s47, s1
	s_cselect_b32 s41, s46, s0
	s_cselect_b32 s82, s49, s51
	s_cselect_b32 s83, s48, s50
	s_add_u32 s0, s0, 0x40080
	s_addc_u32 s1, s1, 0
	s_add_u32 s84, s50, 0x100
	v_mov_b32_e32 v2, 0
	s_addc_u32 s85, s51, 0
	s_mov_b32 s50, 0
	v_mov_b32_e32 v3, v2
	v_mov_b32_e32 v4, v2
	v_mov_b32_e32 v5, v2
	v_mov_b32_e32 v6, v2
	v_mov_b32_e32 v7, v2
	v_mov_b32_e32 v8, v2
	v_mov_b32_e32 v9, v2
	v_mov_b32_e32 v18, v2
	v_mov_b32_e32 v19, v2
	v_mov_b32_e32 v20, v2
	v_mov_b32_e32 v21, v2
	v_mov_b32_e32 v22, v2
	v_mov_b32_e32 v23, v2
	v_mov_b32_e32 v24, v2
	v_mov_b32_e32 v25, v2
	v_mov_b32_e32 v34, v2
	v_mov_b32_e32 v35, v2
	v_mov_b32_e32 v36, v2
	v_mov_b32_e32 v37, v2
	v_mov_b32_e32 v38, v2
	v_mov_b32_e32 v39, v2
	v_mov_b32_e32 v40, v2
	v_mov_b32_e32 v41, v2
	v_mov_b32_e32 v50, v2
	v_mov_b32_e32 v51, v2
	v_mov_b32_e32 v52, v2
	v_mov_b32_e32 v53, v2
	v_mov_b32_e32 v54, v2
	v_mov_b32_e32 v55, v2
	v_mov_b32_e32 v56, v2
	v_mov_b32_e32 v57, v2
	v_mov_b32_e32 v10, v2
	v_mov_b32_e32 v11, v2
	v_mov_b32_e32 v12, v2
	v_mov_b32_e32 v13, v2
	v_mov_b32_e32 v14, v2
	v_mov_b32_e32 v15, v2
	v_mov_b32_e32 v16, v2
	v_mov_b32_e32 v17, v2
	v_mov_b32_e32 v26, v2
	v_mov_b32_e32 v27, v2
	v_mov_b32_e32 v28, v2
	v_mov_b32_e32 v29, v2
	v_mov_b32_e32 v30, v2
	v_mov_b32_e32 v31, v2
	v_mov_b32_e32 v32, v2
	v_mov_b32_e32 v33, v2
	v_mov_b32_e32 v42, v2
	v_mov_b32_e32 v43, v2
	v_mov_b32_e32 v44, v2
	v_mov_b32_e32 v45, v2
	v_mov_b32_e32 v46, v2
	v_mov_b32_e32 v47, v2
	v_mov_b32_e32 v48, v2
	v_mov_b32_e32 v49, v2
	v_mov_b32_e32 v58, v2
	v_mov_b32_e32 v59, v2
	v_mov_b32_e32 v60, v2
	v_mov_b32_e32 v61, v2
	v_mov_b32_e32 v62, v2
	v_mov_b32_e32 v63, v2
	v_mov_b32_e32 v64, v2
	v_mov_b32_e32 v65, v2
	v_mov_b32_e32 v66, v2
	v_mov_b32_e32 v67, v2
	v_mov_b32_e32 v68, v2
	v_mov_b32_e32 v69, v2
	v_mov_b32_e32 v70, v2
	v_mov_b32_e32 v71, v2
	v_mov_b32_e32 v72, v2
	v_mov_b32_e32 v73, v2
	v_mov_b32_e32 v82, v2
	v_mov_b32_e32 v83, v2
	v_mov_b32_e32 v84, v2
	v_mov_b32_e32 v85, v2
	v_mov_b32_e32 v86, v2
	v_mov_b32_e32 v87, v2
	v_mov_b32_e32 v88, v2
	v_mov_b32_e32 v89, v2
	v_mov_b32_e32 v98, v2
	v_mov_b32_e32 v99, v2
	v_mov_b32_e32 v100, v2
	v_mov_b32_e32 v101, v2
	v_mov_b32_e32 v102, v2
	v_mov_b32_e32 v103, v2
	v_mov_b32_e32 v104, v2
	v_mov_b32_e32 v105, v2
	v_mov_b32_e32 v114, v2
	v_mov_b32_e32 v115, v2
	v_mov_b32_e32 v116, v2
	v_mov_b32_e32 v117, v2
	v_mov_b32_e32 v118, v2
	v_mov_b32_e32 v119, v2
	v_mov_b32_e32 v120, v2
	v_mov_b32_e32 v121, v2
	v_mov_b32_e32 v74, v2
	v_mov_b32_e32 v75, v2
	v_mov_b32_e32 v76, v2
	v_mov_b32_e32 v77, v2
	v_mov_b32_e32 v78, v2
	v_mov_b32_e32 v79, v2
	v_mov_b32_e32 v80, v2
	v_mov_b32_e32 v81, v2
	v_mov_b32_e32 v90, v2
	v_mov_b32_e32 v91, v2
	v_mov_b32_e32 v92, v2
	v_mov_b32_e32 v93, v2
	v_mov_b32_e32 v94, v2
	v_mov_b32_e32 v95, v2
	v_mov_b32_e32 v96, v2
	v_mov_b32_e32 v97, v2
	v_mov_b32_e32 v106, v2
	v_mov_b32_e32 v107, v2
	v_mov_b32_e32 v108, v2
	v_mov_b32_e32 v109, v2
	v_mov_b32_e32 v110, v2
	v_mov_b32_e32 v111, v2
	v_mov_b32_e32 v112, v2
	v_mov_b32_e32 v113, v2
	v_mov_b32_e32 v126, v2
	v_mov_b32_e32 v127, v2
	v_mov_b32_e32 v128, v2
	v_mov_b32_e32 v129, v2
	v_mov_b32_e32 v122, v2
	v_mov_b32_e32 v123, v2
	v_mov_b32_e32 v124, v2
	v_mov_b32_e32 v125, v2
	v_readfirstlane_b32 s96, v193
	s_lshr_b32 s96, s96, 8
	s_cmp_eq_u32 s96, 0
	s_cbranch_scc0 .Lnp_912
	s_setprio 1
